# qkconv conv loop: prefetch distance 2 (three register sets, unrolled by 3) with scalar row/halo/address arithmetic
# speedup vs baseline: 1.0025x; 1.0025x over previous
.LBB0_1608:
	s_or_b64 exec, exec, s[18:19]
	v_lshl_add_u32 v2, s2, 9, v128
	s_mov_b32 s0, 0x240000
	v_cmp_gt_i32_e32 vcc, s0, v2
	s_and_saveexec_b64 s[6:7], vcc
	v_readlane_b32 s36, v252, 16
	v_readlane_b32 s50, v252, 30
	v_readlane_b32 s51, v252, 31
	v_readlane_b32 s37, v252, 17
	v_readlane_b32 s38, v252, 18
	v_readlane_b32 s39, v252, 19
	v_readlane_b32 s40, v252, 20
	v_readlane_b32 s41, v252, 21
	v_readlane_b32 s42, v252, 22
	v_readlane_b32 s43, v252, 23
	v_readlane_b32 s44, v252, 24
	v_readlane_b32 s45, v252, 25
	v_readlane_b32 s46, v252, 26
	v_readlane_b32 s47, v252, 27
	v_readlane_b32 s48, v252, 28
	v_readlane_b32 s49, v252, 29
	s_cbranch_execz .LBB0_1611
	v_lshlrev_b32_e32 v0, 3, v128
	s_mov_b64 s[26:27], s[50:51]
	s_lshl_b32 s14, s22, 9
	v_lshl_add_u32 v3, s2, 12, v0
	s_lshl_b32 s15, s22, 12
	s_mov_b64 s[8:9], 0
	s_movk_i32 s16, 0x4000
	s_waitcnt vmcnt(2)
	v_mov_b32_e32 v4, 0xff
	v_mov_b32_e32 v5, 0x7ff
	v_mov_b32_e32 v6, 0x100
	v_mov_b32_e32 v7, 0x800
	v_mov_b32_e32 v1, 0
	s_mov_b64 s[10:11], 0x1000
	s_mov_b64 s[12:13], 0x2000
	s_movk_i32 s17, 0x2000
	s_movk_i32 s18, 0x1ff
	v_mov_b32_e32 v8, 0x3e000000
	s_mov_b32 s19, 0x23ffff
	v_and_b32_e32 v9, 0x3f8, v3
	v_lshlrev_b32_e32 v0, 2, v9
	v_add_u32_e32 v106, 0x1000, v0
	v_add_u32_e32 v107, 0x2000, v0
	global_load_dwordx4 v[74:77], v0, s[72:73]
	global_load_dwordx4 v[78:81], v0, s[72:73] offset:16
	global_load_dwordx4 v[82:85], v0, s[26:27]
	global_load_dwordx4 v[86:89], v0, s[26:27] offset:16
	global_load_dwordx4 v[90:93], v106, s[26:27]
	global_load_dwordx4 v[94:97], v106, s[26:27] offset:16
	global_load_dwordx4 v[98:101], v107, s[26:27]
	global_load_dwordx4 v[102:105], v107, s[26:27] offset:16
	v_lshlrev_b32_e32 v68, 1, v9
	v_cmp_lt_u32_e64 s[0:1], s18, v9
	v_readfirstlane_b32 s17, v128
	s_lshl_b32 s98, s2, 9
	v_cndmask_b32_e64 v67, 1.0, v8, s[0:1]
	s_lshr_b32 s17, s17, 7
	s_mov_b32 s99, 0
	s_lshr_b32 s8, s98, 7
	s_add_i32 s8, s8, s17
	s_cmp_lt_i32 s8, s16
	s_movk_i32 s9, 0xff
	s_cselect_b32 s9, 0x7ff, s9
	s_and_b32 s0, s8, s9
	s_cmp_lg_u32 s0, 0
	s_cselect_b32 s1, 1, 0
	s_cmp_lg_u32 s0, s9
	s_cselect_b32 s9, 1, 0
	s_lshl_b32 s0, s9, 1
	s_or_b32 s0, s0, s1
	s_andn2_b32 s99, s99, 3
	s_or_b32 s99, s99, s0
	s_sub_i32 s0, s8, s1
	s_lshl_b32 s0, s0, 11
	s_add_u32 s0, s4, s0
	s_addc_u32 s1, s5, 0
	global_load_dwordx4 v[46:49], v68, s[0:1]
	s_lshl_b32 s0, s8, 11
	s_add_u32 s0, s4, s0
	s_addc_u32 s1, s5, 0
	global_load_dwordx4 v[50:53], v68, s[0:1]
	s_lshl_b32 s10, s8, 11
	s_add_u32 s10, s88, s10
	s_addc_u32 s11, s89, 0
	s_add_i32 s0, s8, s9
	s_lshl_b32 s0, s0, 11
	s_add_u32 s0, s4, s0
	s_addc_u32 s1, s5, 0
	global_load_dwordx4 v[42:45], v68, s[0:1]
	s_add_i32 s98, s98, s14
	s_cmp_lt_i32 s98, 0x240000
	s_cbranch_scc0 .Lqkc_tail_x1
	s_lshr_b32 s8, s98, 7
	s_add_i32 s8, s8, s17
	s_cmp_lt_i32 s8, s16
	s_movk_i32 s9, 0xff
	s_cselect_b32 s9, 0x7ff, s9
	s_and_b32 s0, s8, s9
	s_cmp_lg_u32 s0, 0
	s_cselect_b32 s1, 1, 0
	s_cmp_lg_u32 s0, s9
	s_cselect_b32 s9, 1, 0
	s_lshl_b32 s0, s9, 1
	s_or_b32 s0, s0, s1
	s_lshl_b32 s0, s0, 2
	s_andn2_b32 s99, s99, 12
	s_or_b32 s99, s99, s0
	s_sub_i32 s0, s8, s1
	s_lshl_b32 s0, s0, 11
	s_add_u32 s0, s4, s0
	s_addc_u32 s1, s5, 0
	global_load_dwordx4 v[114:117], v68, s[0:1]
	s_lshl_b32 s0, s8, 11
	s_add_u32 s0, s4, s0
	s_addc_u32 s1, s5, 0
	global_load_dwordx4 v[118:121], v68, s[0:1]
	s_lshl_b32 s12, s8, 11
	s_add_u32 s12, s88, s12
	s_addc_u32 s13, s89, 0
	s_add_i32 s0, s8, s9
	s_lshl_b32 s0, s0, 11
	s_add_u32 s0, s4, s0
	s_addc_u32 s1, s5, 0
	global_load_dwordx4 v[122:125], v68, s[0:1]
	s_add_i32 s98, s98, s14
	s_cmp_lt_i32 s98, 0x240000
	s_cbranch_scc0 .Lqkc_tail_xy
	s_lshr_b32 s8, s98, 7
	s_add_i32 s8, s8, s17
	s_cmp_lt_i32 s8, s16
	s_movk_i32 s9, 0xff
	s_cselect_b32 s9, 0x7ff, s9
	s_and_b32 s0, s8, s9
	s_cmp_lg_u32 s0, 0
	s_cselect_b32 s1, 1, 0
	s_cmp_lg_u32 s0, s9
	s_cselect_b32 s9, 1, 0
	s_lshl_b32 s0, s9, 1
	s_or_b32 s0, s0, s1
	s_lshl_b32 s0, s0, 4
	s_andn2_b32 s99, s99, 48
	s_or_b32 s99, s99, s0
	s_sub_i32 s0, s8, s1
	s_lshl_b32 s0, s0, 11
	s_add_u32 s0, s4, s0
	s_addc_u32 s1, s5, 0
	global_load_dwordx4 v[26:29], v68, s[0:1]
	s_lshl_b32 s0, s8, 11
	s_add_u32 s0, s4, s0
	s_addc_u32 s1, s5, 0
	global_load_dwordx4 v[30:33], v68, s[0:1]
	s_lshl_b32 s100, s8, 11
	s_add_u32 s100, s88, s100
	s_addc_u32 s101, s89, 0
	s_add_i32 s0, s8, s9
	s_lshl_b32 s0, s0, 11
	s_add_u32 s0, s4, s0
	s_addc_u32 s1, s5, 0
	global_load_dwordx4 v[34:37], v68, s[0:1]
	s_add_i32 s98, s98, s14
	s_waitcnt vmcnt(3)
.Lqkc_loop:
	s_waitcnt vmcnt(10)
	s_bitcmp1_b32 s99, 0
	s_cbranch_scc0 .Lqkc_off0_1
	v_lshlrev_b32_e32 v59, 16, v46
	v_and_b32_e32 v60, 0xffff0000, v46
	v_lshlrev_b32_e32 v61, 16, v47
	v_and_b32_e32 v62, 0xffff0000, v47
	v_lshlrev_b32_e32 v63, 16, v48
	v_and_b32_e32 v64, 0xffff0000, v48
	v_lshlrev_b32_e32 v65, 16, v49
	v_and_b32_e32 v66, 0xffff0000, v49
	v_fma_f32 v10, v82, v59, v74
	v_fma_f32 v11, v83, v60, v75
	v_fma_f32 v12, v84, v61, v76
	v_fma_f32 v13, v85, v62, v77
	v_fma_f32 v14, v86, v63, v78
	v_fma_f32 v15, v87, v64, v79
	v_fma_f32 v16, v88, v65, v80
	v_fma_f32 v17, v89, v66, v81
	s_branch .Lqkc_j0_1

.Lqkc_j0_1:
	s_waitcnt vmcnt(9)
	v_lshlrev_b32_e32 v59, 16, v50
	v_and_b32_e32 v60, 0xffff0000, v50
	v_lshlrev_b32_e32 v61, 16, v51
	v_and_b32_e32 v62, 0xffff0000, v51
	v_lshlrev_b32_e32 v63, 16, v52
	v_and_b32_e32 v64, 0xffff0000, v52
	v_lshlrev_b32_e32 v65, 16, v53
	v_and_b32_e32 v66, 0xffff0000, v53
	v_fmac_f32_e32 v10, v90, v59
	v_fmac_f32_e32 v11, v91, v60
	v_fmac_f32_e32 v12, v92, v61
	v_fmac_f32_e32 v13, v93, v62
	v_fmac_f32_e32 v14, v94, v63
	v_fmac_f32_e32 v15, v95, v64
	v_fmac_f32_e32 v16, v96, v65
	v_fmac_f32_e32 v17, v97, v66
	s_waitcnt vmcnt(8)
	s_bitcmp1_b32 s99, 1
	s_cbranch_scc0 .Lqkc_off2_1
	v_lshlrev_b32_e32 v59, 16, v42
	v_and_b32_e32 v60, 0xffff0000, v42
	v_lshlrev_b32_e32 v61, 16, v43
	v_and_b32_e32 v62, 0xffff0000, v43
	v_lshlrev_b32_e32 v63, 16, v44
	v_and_b32_e32 v64, 0xffff0000, v44
	v_lshlrev_b32_e32 v65, 16, v45
	v_and_b32_e32 v66, 0xffff0000, v45
	v_fmac_f32_e32 v10, v98, v59
	v_fmac_f32_e32 v11, v99, v60
	v_fmac_f32_e32 v12, v100, v61
	v_fmac_f32_e32 v13, v101, v62
	v_fmac_f32_e32 v14, v102, v63
	v_fmac_f32_e32 v15, v103, v64
	v_fmac_f32_e32 v16, v104, v65
	v_fmac_f32_e32 v17, v105, v66
.Lqkc_off2_1:
	v_mul_f32_e32 v18, 0xbfb8aa3b, v10
	v_mul_f32_e32 v19, 0xbfb8aa3b, v11
	v_mul_f32_e32 v20, 0xbfb8aa3b, v12
	v_mul_f32_e32 v21, 0xbfb8aa3b, v13
	v_mul_f32_e32 v22, 0xbfb8aa3b, v14
	v_mul_f32_e32 v23, 0xbfb8aa3b, v15
	v_mul_f32_e32 v24, 0xbfb8aa3b, v16
	v_mul_f32_e32 v25, 0xbfb8aa3b, v17
	v_exp_f32_e32 v18, v18
	v_exp_f32_e32 v19, v19
	v_exp_f32_e32 v20, v20
	v_exp_f32_e32 v21, v21
	v_exp_f32_e32 v22, v22
	v_exp_f32_e32 v23, v23
	v_exp_f32_e32 v24, v24
	v_exp_f32_e32 v25, v25
	v_add_f32_e32 v18, 1.0, v18
	v_add_f32_e32 v19, 1.0, v19
	v_add_f32_e32 v20, 1.0, v20
	v_add_f32_e32 v21, 1.0, v21
	v_add_f32_e32 v22, 1.0, v22
	v_add_f32_e32 v23, 1.0, v23
	v_add_f32_e32 v24, 1.0, v24
	v_add_f32_e32 v25, 1.0, v25
	v_rcp_f32_e32 v18, v18
	v_rcp_f32_e32 v19, v19
	v_rcp_f32_e32 v20, v20
	v_rcp_f32_e32 v21, v21
	v_rcp_f32_e32 v22, v22
	v_rcp_f32_e32 v23, v23
	v_rcp_f32_e32 v24, v24
	v_rcp_f32_e32 v25, v25
	v_mul_f32_e32 v18, v10, v18
	v_mul_f32_e32 v19, v11, v19
	v_mul_f32_e32 v20, v12, v20
	v_mul_f32_e32 v21, v13, v21
	v_mul_f32_e32 v22, v14, v22
	v_mul_f32_e32 v23, v15, v23
	v_mul_f32_e32 v24, v16, v24
	v_mul_f32_e32 v25, v17, v25
	v_mul_f32_e32 v18, v67, v18
	v_mul_f32_e32 v19, v67, v19
	v_mul_f32_e32 v20, v67, v20
	v_mul_f32_e32 v21, v67, v21
	v_mul_f32_e32 v22, v67, v22
	v_mul_f32_e32 v23, v67, v23
	v_mul_f32_e32 v24, v67, v24
	v_mul_f32_e32 v25, v67, v25
	v_cvt_pk_bf16_f32 v10, v18, v19
	v_cvt_pk_bf16_f32 v11, v20, v21
	v_cvt_pk_bf16_f32 v12, v22, v23
	v_cvt_pk_bf16_f32 v13, v24, v25
	global_store_dwordx4 v68, v[10:13], s[10:11]
	s_cmp_lt_i32 s98, 0x240000
	s_cbranch_scc0 .Lqkc_tail_yz
	s_lshr_b32 s8, s98, 7
	s_add_i32 s8, s8, s17
	s_cmp_lt_i32 s8, s16
	s_movk_i32 s9, 0xff
	s_cselect_b32 s9, 0x7ff, s9
	s_and_b32 s0, s8, s9
	s_cmp_lg_u32 s0, 0
	s_cselect_b32 s1, 1, 0
	s_cmp_lg_u32 s0, s9
	s_cselect_b32 s9, 1, 0
	s_lshl_b32 s0, s9, 1
	s_or_b32 s0, s0, s1
	s_andn2_b32 s99, s99, 3
	s_or_b32 s99, s99, s0
	s_sub_i32 s0, s8, s1
	s_lshl_b32 s0, s0, 11
	s_add_u32 s0, s4, s0
	s_addc_u32 s1, s5, 0
	global_load_dwordx4 v[46:49], v68, s[0:1]
	s_lshl_b32 s0, s8, 11
	s_add_u32 s0, s4, s0
	s_addc_u32 s1, s5, 0
	global_load_dwordx4 v[50:53], v68, s[0:1]
	s_lshl_b32 s10, s8, 11
	s_add_u32 s10, s88, s10
	s_addc_u32 s11, s89, 0
	s_add_i32 s0, s8, s9
	s_lshl_b32 s0, s0, 11
	s_add_u32 s0, s4, s0
	s_addc_u32 s1, s5, 0
	global_load_dwordx4 v[42:45], v68, s[0:1]
	s_add_i32 s98, s98, s14
	s_waitcnt vmcnt(10)
	s_bitcmp1_b32 s99, 2
	s_cbranch_scc0 .Lqkc_off0_2
	v_lshlrev_b32_e32 v59, 16, v114
	v_and_b32_e32 v60, 0xffff0000, v114
	v_lshlrev_b32_e32 v61, 16, v115
	v_and_b32_e32 v62, 0xffff0000, v115
	v_lshlrev_b32_e32 v63, 16, v116
	v_and_b32_e32 v64, 0xffff0000, v116
	v_lshlrev_b32_e32 v65, 16, v117
	v_and_b32_e32 v66, 0xffff0000, v117
	v_fma_f32 v10, v82, v59, v74
	v_fma_f32 v11, v83, v60, v75
	v_fma_f32 v12, v84, v61, v76
	v_fma_f32 v13, v85, v62, v77
	v_fma_f32 v14, v86, v63, v78
	v_fma_f32 v15, v87, v64, v79
	v_fma_f32 v16, v88, v65, v80
	v_fma_f32 v17, v89, v66, v81
	s_branch .Lqkc_j0_2

.Lqkc_j0_2:
	s_waitcnt vmcnt(9)
	v_lshlrev_b32_e32 v59, 16, v118
	v_and_b32_e32 v60, 0xffff0000, v118
	v_lshlrev_b32_e32 v61, 16, v119
	v_and_b32_e32 v62, 0xffff0000, v119
	v_lshlrev_b32_e32 v63, 16, v120
	v_and_b32_e32 v64, 0xffff0000, v120
	v_lshlrev_b32_e32 v65, 16, v121
	v_and_b32_e32 v66, 0xffff0000, v121
	v_fmac_f32_e32 v10, v90, v59
	v_fmac_f32_e32 v11, v91, v60
	v_fmac_f32_e32 v12, v92, v61
	v_fmac_f32_e32 v13, v93, v62
	v_fmac_f32_e32 v14, v94, v63
	v_fmac_f32_e32 v15, v95, v64
	v_fmac_f32_e32 v16, v96, v65
	v_fmac_f32_e32 v17, v97, v66
	s_waitcnt vmcnt(8)
	s_bitcmp1_b32 s99, 3
	s_cbranch_scc0 .Lqkc_off2_2
	v_lshlrev_b32_e32 v59, 16, v122
	v_and_b32_e32 v60, 0xffff0000, v122
	v_lshlrev_b32_e32 v61, 16, v123
	v_and_b32_e32 v62, 0xffff0000, v123
	v_lshlrev_b32_e32 v63, 16, v124
	v_and_b32_e32 v64, 0xffff0000, v124
	v_lshlrev_b32_e32 v65, 16, v125
	v_and_b32_e32 v66, 0xffff0000, v125
	v_fmac_f32_e32 v10, v98, v59
	v_fmac_f32_e32 v11, v99, v60
	v_fmac_f32_e32 v12, v100, v61
	v_fmac_f32_e32 v13, v101, v62
	v_fmac_f32_e32 v14, v102, v63
	v_fmac_f32_e32 v15, v103, v64
	v_fmac_f32_e32 v16, v104, v65
	v_fmac_f32_e32 v17, v105, v66
.Lqkc_off2_2:
	v_mul_f32_e32 v18, 0xbfb8aa3b, v10
	v_mul_f32_e32 v19, 0xbfb8aa3b, v11
	v_mul_f32_e32 v20, 0xbfb8aa3b, v12
	v_mul_f32_e32 v21, 0xbfb8aa3b, v13
	v_mul_f32_e32 v22, 0xbfb8aa3b, v14
	v_mul_f32_e32 v23, 0xbfb8aa3b, v15
	v_mul_f32_e32 v24, 0xbfb8aa3b, v16
	v_mul_f32_e32 v25, 0xbfb8aa3b, v17
	v_exp_f32_e32 v18, v18
	v_exp_f32_e32 v19, v19
	v_exp_f32_e32 v20, v20
	v_exp_f32_e32 v21, v21
	v_exp_f32_e32 v22, v22
	v_exp_f32_e32 v23, v23
	v_exp_f32_e32 v24, v24
	v_exp_f32_e32 v25, v25
	v_add_f32_e32 v18, 1.0, v18
	v_add_f32_e32 v19, 1.0, v19
	v_add_f32_e32 v20, 1.0, v20
	v_add_f32_e32 v21, 1.0, v21
	v_add_f32_e32 v22, 1.0, v22
	v_add_f32_e32 v23, 1.0, v23
	v_add_f32_e32 v24, 1.0, v24
	v_add_f32_e32 v25, 1.0, v25
	v_rcp_f32_e32 v18, v18
	v_rcp_f32_e32 v19, v19
	v_rcp_f32_e32 v20, v20
	v_rcp_f32_e32 v21, v21
	v_rcp_f32_e32 v22, v22
	v_rcp_f32_e32 v23, v23
	v_rcp_f32_e32 v24, v24
	v_rcp_f32_e32 v25, v25
	v_mul_f32_e32 v18, v10, v18
	v_mul_f32_e32 v19, v11, v19
	v_mul_f32_e32 v20, v12, v20
	v_mul_f32_e32 v21, v13, v21
	v_mul_f32_e32 v22, v14, v22
	v_mul_f32_e32 v23, v15, v23
	v_mul_f32_e32 v24, v16, v24
	v_mul_f32_e32 v25, v17, v25
	v_mul_f32_e32 v18, v67, v18
	v_mul_f32_e32 v19, v67, v19
	v_mul_f32_e32 v20, v67, v20
	v_mul_f32_e32 v21, v67, v21
	v_mul_f32_e32 v22, v67, v22
	v_mul_f32_e32 v23, v67, v23
	v_mul_f32_e32 v24, v67, v24
	v_mul_f32_e32 v25, v67, v25
	v_cvt_pk_bf16_f32 v10, v18, v19
	v_cvt_pk_bf16_f32 v11, v20, v21
	v_cvt_pk_bf16_f32 v12, v22, v23
	v_cvt_pk_bf16_f32 v13, v24, v25
	global_store_dwordx4 v68, v[10:13], s[12:13]
	s_cmp_lt_i32 s98, 0x240000
	s_cbranch_scc0 .Lqkc_tail_zx
	s_lshr_b32 s8, s98, 7
	s_add_i32 s8, s8, s17
	s_cmp_lt_i32 s8, s16
	s_movk_i32 s9, 0xff
	s_cselect_b32 s9, 0x7ff, s9
	s_and_b32 s0, s8, s9
	s_cmp_lg_u32 s0, 0
	s_cselect_b32 s1, 1, 0
	s_cmp_lg_u32 s0, s9
	s_cselect_b32 s9, 1, 0
	s_lshl_b32 s0, s9, 1
	s_or_b32 s0, s0, s1
	s_lshl_b32 s0, s0, 2
	s_andn2_b32 s99, s99, 12
	s_or_b32 s99, s99, s0
	s_sub_i32 s0, s8, s1
	s_lshl_b32 s0, s0, 11
	s_add_u32 s0, s4, s0
	s_addc_u32 s1, s5, 0
	global_load_dwordx4 v[114:117], v68, s[0:1]
	s_lshl_b32 s0, s8, 11
	s_add_u32 s0, s4, s0
	s_addc_u32 s1, s5, 0
	global_load_dwordx4 v[118:121], v68, s[0:1]
	s_lshl_b32 s12, s8, 11
	s_add_u32 s12, s88, s12
	s_addc_u32 s13, s89, 0
	s_add_i32 s0, s8, s9
	s_lshl_b32 s0, s0, 11
	s_add_u32 s0, s4, s0
	s_addc_u32 s1, s5, 0
	global_load_dwordx4 v[122:125], v68, s[0:1]
	s_add_i32 s98, s98, s14
	s_waitcnt vmcnt(10)
	s_bitcmp1_b32 s99, 4
	s_cbranch_scc0 .Lqkc_off0_3
	v_lshlrev_b32_e32 v59, 16, v26
	v_and_b32_e32 v60, 0xffff0000, v26
	v_lshlrev_b32_e32 v61, 16, v27
	v_and_b32_e32 v62, 0xffff0000, v27
	v_lshlrev_b32_e32 v63, 16, v28
	v_and_b32_e32 v64, 0xffff0000, v28
	v_lshlrev_b32_e32 v65, 16, v29
	v_and_b32_e32 v66, 0xffff0000, v29
	v_fma_f32 v10, v82, v59, v74
	v_fma_f32 v11, v83, v60, v75
	v_fma_f32 v12, v84, v61, v76
	v_fma_f32 v13, v85, v62, v77
	v_fma_f32 v14, v86, v63, v78
	v_fma_f32 v15, v87, v64, v79
	v_fma_f32 v16, v88, v65, v80
	v_fma_f32 v17, v89, v66, v81
	s_branch .Lqkc_j0_3

.Lqkc_j0_3:
	s_waitcnt vmcnt(9)
	v_lshlrev_b32_e32 v59, 16, v30
	v_and_b32_e32 v60, 0xffff0000, v30
	v_lshlrev_b32_e32 v61, 16, v31
	v_and_b32_e32 v62, 0xffff0000, v31
	v_lshlrev_b32_e32 v63, 16, v32
	v_and_b32_e32 v64, 0xffff0000, v32
	v_lshlrev_b32_e32 v65, 16, v33
	v_and_b32_e32 v66, 0xffff0000, v33
	v_fmac_f32_e32 v10, v90, v59
	v_fmac_f32_e32 v11, v91, v60
	v_fmac_f32_e32 v12, v92, v61
	v_fmac_f32_e32 v13, v93, v62
	v_fmac_f32_e32 v14, v94, v63
	v_fmac_f32_e32 v15, v95, v64
	v_fmac_f32_e32 v16, v96, v65
	v_fmac_f32_e32 v17, v97, v66
	s_waitcnt vmcnt(8)
	s_bitcmp1_b32 s99, 5
	s_cbranch_scc0 .Lqkc_off2_3
	v_lshlrev_b32_e32 v59, 16, v34
	v_and_b32_e32 v60, 0xffff0000, v34
	v_lshlrev_b32_e32 v61, 16, v35
	v_and_b32_e32 v62, 0xffff0000, v35
	v_lshlrev_b32_e32 v63, 16, v36
	v_and_b32_e32 v64, 0xffff0000, v36
	v_lshlrev_b32_e32 v65, 16, v37
	v_and_b32_e32 v66, 0xffff0000, v37
	v_fmac_f32_e32 v10, v98, v59
	v_fmac_f32_e32 v11, v99, v60
	v_fmac_f32_e32 v12, v100, v61
	v_fmac_f32_e32 v13, v101, v62
	v_fmac_f32_e32 v14, v102, v63
	v_fmac_f32_e32 v15, v103, v64
	v_fmac_f32_e32 v16, v104, v65
	v_fmac_f32_e32 v17, v105, v66
.Lqkc_off2_3:
	v_mul_f32_e32 v18, 0xbfb8aa3b, v10
	v_mul_f32_e32 v19, 0xbfb8aa3b, v11
	v_mul_f32_e32 v20, 0xbfb8aa3b, v12
	v_mul_f32_e32 v21, 0xbfb8aa3b, v13
	v_mul_f32_e32 v22, 0xbfb8aa3b, v14
	v_mul_f32_e32 v23, 0xbfb8aa3b, v15
	v_mul_f32_e32 v24, 0xbfb8aa3b, v16
	v_mul_f32_e32 v25, 0xbfb8aa3b, v17
	v_exp_f32_e32 v18, v18
	v_exp_f32_e32 v19, v19
	v_exp_f32_e32 v20, v20
	v_exp_f32_e32 v21, v21
	v_exp_f32_e32 v22, v22
	v_exp_f32_e32 v23, v23
	v_exp_f32_e32 v24, v24
	v_exp_f32_e32 v25, v25
	v_add_f32_e32 v18, 1.0, v18
	v_add_f32_e32 v19, 1.0, v19
	v_add_f32_e32 v20, 1.0, v20
	v_add_f32_e32 v21, 1.0, v21
	v_add_f32_e32 v22, 1.0, v22
	v_add_f32_e32 v23, 1.0, v23
	v_add_f32_e32 v24, 1.0, v24
	v_add_f32_e32 v25, 1.0, v25
	v_rcp_f32_e32 v18, v18
	v_rcp_f32_e32 v19, v19
	v_rcp_f32_e32 v20, v20
	v_rcp_f32_e32 v21, v21
	v_rcp_f32_e32 v22, v22
	v_rcp_f32_e32 v23, v23
	v_rcp_f32_e32 v24, v24
	v_rcp_f32_e32 v25, v25
	v_mul_f32_e32 v18, v10, v18
	v_mul_f32_e32 v19, v11, v19
	v_mul_f32_e32 v20, v12, v20
	v_mul_f32_e32 v21, v13, v21
	v_mul_f32_e32 v22, v14, v22
	v_mul_f32_e32 v23, v15, v23
	v_mul_f32_e32 v24, v16, v24
	v_mul_f32_e32 v25, v17, v25
	v_mul_f32_e32 v18, v67, v18
	v_mul_f32_e32 v19, v67, v19
	v_mul_f32_e32 v20, v67, v20
	v_mul_f32_e32 v21, v67, v21
	v_mul_f32_e32 v22, v67, v22
	v_mul_f32_e32 v23, v67, v23
	v_mul_f32_e32 v24, v67, v24
	v_mul_f32_e32 v25, v67, v25
	v_cvt_pk_bf16_f32 v10, v18, v19
	v_cvt_pk_bf16_f32 v11, v20, v21
	v_cvt_pk_bf16_f32 v12, v22, v23
	v_cvt_pk_bf16_f32 v13, v24, v25
	global_store_dwordx4 v68, v[10:13], s[100:101]
	s_cmp_lt_i32 s98, 0x240000
	s_cbranch_scc0 .Lqkc_tail_xy
	s_lshr_b32 s8, s98, 7
	s_add_i32 s8, s8, s17
	s_cmp_lt_i32 s8, s16
	s_movk_i32 s9, 0xff
	s_cselect_b32 s9, 0x7ff, s9
	s_and_b32 s0, s8, s9
	s_cmp_lg_u32 s0, 0
	s_cselect_b32 s1, 1, 0
	s_cmp_lg_u32 s0, s9
	s_cselect_b32 s9, 1, 0
	s_lshl_b32 s0, s9, 1
	s_or_b32 s0, s0, s1
	s_lshl_b32 s0, s0, 4
	s_andn2_b32 s99, s99, 48
	s_or_b32 s99, s99, s0
	s_sub_i32 s0, s8, s1
	s_lshl_b32 s0, s0, 11
	s_add_u32 s0, s4, s0
	s_addc_u32 s1, s5, 0
	global_load_dwordx4 v[26:29], v68, s[0:1]
	s_lshl_b32 s0, s8, 11
	s_add_u32 s0, s4, s0
	s_addc_u32 s1, s5, 0
	global_load_dwordx4 v[30:33], v68, s[0:1]
	s_lshl_b32 s100, s8, 11
	s_add_u32 s100, s88, s100
	s_addc_u32 s101, s89, 0
	s_add_i32 s0, s8, s9
	s_lshl_b32 s0, s0, 11
	s_add_u32 s0, s4, s0
	s_addc_u32 s1, s5, 0
	global_load_dwordx4 v[34:37], v68, s[0:1]
	s_add_i32 s98, s98, s14
	s_branch .Lqkc_loop
.Lqkc_tail_yz:
	s_waitcnt vmcnt(0)
	s_bitcmp1_b32 s99, 2
	s_cbranch_scc0 .Lqkc_off0_4
	v_lshlrev_b32_e32 v59, 16, v114
	v_and_b32_e32 v60, 0xffff0000, v114
	v_lshlrev_b32_e32 v61, 16, v115
	v_and_b32_e32 v62, 0xffff0000, v115
	v_lshlrev_b32_e32 v63, 16, v116
	v_and_b32_e32 v64, 0xffff0000, v116
	v_lshlrev_b32_e32 v65, 16, v117
	v_and_b32_e32 v66, 0xffff0000, v117
	v_fma_f32 v10, v82, v59, v74
	v_fma_f32 v11, v83, v60, v75
	v_fma_f32 v12, v84, v61, v76
	v_fma_f32 v13, v85, v62, v77
	v_fma_f32 v14, v86, v63, v78
	v_fma_f32 v15, v87, v64, v79
	v_fma_f32 v16, v88, v65, v80
	v_fma_f32 v17, v89, v66, v81
	s_branch .Lqkc_j0_4

.Lqkc_j0_4:
	v_lshlrev_b32_e32 v59, 16, v118
	v_and_b32_e32 v60, 0xffff0000, v118
	v_lshlrev_b32_e32 v61, 16, v119
	v_and_b32_e32 v62, 0xffff0000, v119
	v_lshlrev_b32_e32 v63, 16, v120
	v_and_b32_e32 v64, 0xffff0000, v120
	v_lshlrev_b32_e32 v65, 16, v121
	v_and_b32_e32 v66, 0xffff0000, v121
	v_fmac_f32_e32 v10, v90, v59
	v_fmac_f32_e32 v11, v91, v60
	v_fmac_f32_e32 v12, v92, v61
	v_fmac_f32_e32 v13, v93, v62
	v_fmac_f32_e32 v14, v94, v63
	v_fmac_f32_e32 v15, v95, v64
	v_fmac_f32_e32 v16, v96, v65
	v_fmac_f32_e32 v17, v97, v66
	s_bitcmp1_b32 s99, 3
	s_cbranch_scc0 .Lqkc_off2_4
	v_lshlrev_b32_e32 v59, 16, v122
	v_and_b32_e32 v60, 0xffff0000, v122
	v_lshlrev_b32_e32 v61, 16, v123
	v_and_b32_e32 v62, 0xffff0000, v123
	v_lshlrev_b32_e32 v63, 16, v124
	v_and_b32_e32 v64, 0xffff0000, v124
	v_lshlrev_b32_e32 v65, 16, v125
	v_and_b32_e32 v66, 0xffff0000, v125
	v_fmac_f32_e32 v10, v98, v59
	v_fmac_f32_e32 v11, v99, v60
	v_fmac_f32_e32 v12, v100, v61
	v_fmac_f32_e32 v13, v101, v62
	v_fmac_f32_e32 v14, v102, v63
	v_fmac_f32_e32 v15, v103, v64
	v_fmac_f32_e32 v16, v104, v65
	v_fmac_f32_e32 v17, v105, v66
.Lqkc_off2_4:
	v_mul_f32_e32 v18, 0xbfb8aa3b, v10
	v_mul_f32_e32 v19, 0xbfb8aa3b, v11
	v_mul_f32_e32 v20, 0xbfb8aa3b, v12
	v_mul_f32_e32 v21, 0xbfb8aa3b, v13
	v_mul_f32_e32 v22, 0xbfb8aa3b, v14
	v_mul_f32_e32 v23, 0xbfb8aa3b, v15
	v_mul_f32_e32 v24, 0xbfb8aa3b, v16
	v_mul_f32_e32 v25, 0xbfb8aa3b, v17
	v_exp_f32_e32 v18, v18
	v_exp_f32_e32 v19, v19
	v_exp_f32_e32 v20, v20
	v_exp_f32_e32 v21, v21
	v_exp_f32_e32 v22, v22
	v_exp_f32_e32 v23, v23
	v_exp_f32_e32 v24, v24
	v_exp_f32_e32 v25, v25
	v_add_f32_e32 v18, 1.0, v18
	v_add_f32_e32 v19, 1.0, v19
	v_add_f32_e32 v20, 1.0, v20
	v_add_f32_e32 v21, 1.0, v21
	v_add_f32_e32 v22, 1.0, v22
	v_add_f32_e32 v23, 1.0, v23
	v_add_f32_e32 v24, 1.0, v24
	v_add_f32_e32 v25, 1.0, v25
	v_rcp_f32_e32 v18, v18
	v_rcp_f32_e32 v19, v19
	v_rcp_f32_e32 v20, v20
	v_rcp_f32_e32 v21, v21
	v_rcp_f32_e32 v22, v22
	v_rcp_f32_e32 v23, v23
	v_rcp_f32_e32 v24, v24
	v_rcp_f32_e32 v25, v25
	v_mul_f32_e32 v18, v10, v18
	v_mul_f32_e32 v19, v11, v19
	v_mul_f32_e32 v20, v12, v20
	v_mul_f32_e32 v21, v13, v21
	v_mul_f32_e32 v22, v14, v22
	v_mul_f32_e32 v23, v15, v23
	v_mul_f32_e32 v24, v16, v24
	v_mul_f32_e32 v25, v17, v25
	v_mul_f32_e32 v18, v67, v18
	v_mul_f32_e32 v19, v67, v19
	v_mul_f32_e32 v20, v67, v20
	v_mul_f32_e32 v21, v67, v21
	v_mul_f32_e32 v22, v67, v22
	v_mul_f32_e32 v23, v67, v23
	v_mul_f32_e32 v24, v67, v24
	v_mul_f32_e32 v25, v67, v25
	v_cvt_pk_bf16_f32 v10, v18, v19
	v_cvt_pk_bf16_f32 v11, v20, v21
	v_cvt_pk_bf16_f32 v12, v22, v23
	v_cvt_pk_bf16_f32 v13, v24, v25
	global_store_dwordx4 v68, v[10:13], s[12:13]
	s_waitcnt vmcnt(0)
	s_bitcmp1_b32 s99, 4
	s_cbranch_scc0 .Lqkc_off0_5
	v_lshlrev_b32_e32 v59, 16, v26
	v_and_b32_e32 v60, 0xffff0000, v26
	v_lshlrev_b32_e32 v61, 16, v27
	v_and_b32_e32 v62, 0xffff0000, v27
	v_lshlrev_b32_e32 v63, 16, v28
	v_and_b32_e32 v64, 0xffff0000, v28
	v_lshlrev_b32_e32 v65, 16, v29
	v_and_b32_e32 v66, 0xffff0000, v29
	v_fma_f32 v10, v82, v59, v74
	v_fma_f32 v11, v83, v60, v75
	v_fma_f32 v12, v84, v61, v76
	v_fma_f32 v13, v85, v62, v77
	v_fma_f32 v14, v86, v63, v78
	v_fma_f32 v15, v87, v64, v79
	v_fma_f32 v16, v88, v65, v80
	v_fma_f32 v17, v89, v66, v81
	s_branch .Lqkc_j0_5

.Lqkc_j0_5:
	v_lshlrev_b32_e32 v59, 16, v30
	v_and_b32_e32 v60, 0xffff0000, v30
	v_lshlrev_b32_e32 v61, 16, v31
	v_and_b32_e32 v62, 0xffff0000, v31
	v_lshlrev_b32_e32 v63, 16, v32
	v_and_b32_e32 v64, 0xffff0000, v32
	v_lshlrev_b32_e32 v65, 16, v33
	v_and_b32_e32 v66, 0xffff0000, v33
	v_fmac_f32_e32 v10, v90, v59
	v_fmac_f32_e32 v11, v91, v60
	v_fmac_f32_e32 v12, v92, v61
	v_fmac_f32_e32 v13, v93, v62
	v_fmac_f32_e32 v14, v94, v63
	v_fmac_f32_e32 v15, v95, v64
	v_fmac_f32_e32 v16, v96, v65
	v_fmac_f32_e32 v17, v97, v66
	s_bitcmp1_b32 s99, 5
	s_cbranch_scc0 .Lqkc_off2_5
	v_lshlrev_b32_e32 v59, 16, v34
	v_and_b32_e32 v60, 0xffff0000, v34
	v_lshlrev_b32_e32 v61, 16, v35
	v_and_b32_e32 v62, 0xffff0000, v35
	v_lshlrev_b32_e32 v63, 16, v36
	v_and_b32_e32 v64, 0xffff0000, v36
	v_lshlrev_b32_e32 v65, 16, v37
	v_and_b32_e32 v66, 0xffff0000, v37
	v_fmac_f32_e32 v10, v98, v59
	v_fmac_f32_e32 v11, v99, v60
	v_fmac_f32_e32 v12, v100, v61
	v_fmac_f32_e32 v13, v101, v62
	v_fmac_f32_e32 v14, v102, v63
	v_fmac_f32_e32 v15, v103, v64
	v_fmac_f32_e32 v16, v104, v65
	v_fmac_f32_e32 v17, v105, v66
.Lqkc_off2_5:
	v_mul_f32_e32 v18, 0xbfb8aa3b, v10
	v_mul_f32_e32 v19, 0xbfb8aa3b, v11
	v_mul_f32_e32 v20, 0xbfb8aa3b, v12
	v_mul_f32_e32 v21, 0xbfb8aa3b, v13
	v_mul_f32_e32 v22, 0xbfb8aa3b, v14
	v_mul_f32_e32 v23, 0xbfb8aa3b, v15
	v_mul_f32_e32 v24, 0xbfb8aa3b, v16
	v_mul_f32_e32 v25, 0xbfb8aa3b, v17
	v_exp_f32_e32 v18, v18
	v_exp_f32_e32 v19, v19
	v_exp_f32_e32 v20, v20
	v_exp_f32_e32 v21, v21
	v_exp_f32_e32 v22, v22
	v_exp_f32_e32 v23, v23
	v_exp_f32_e32 v24, v24
	v_exp_f32_e32 v25, v25
	v_add_f32_e32 v18, 1.0, v18
	v_add_f32_e32 v19, 1.0, v19
	v_add_f32_e32 v20, 1.0, v20
	v_add_f32_e32 v21, 1.0, v21
	v_add_f32_e32 v22, 1.0, v22
	v_add_f32_e32 v23, 1.0, v23
	v_add_f32_e32 v24, 1.0, v24
	v_add_f32_e32 v25, 1.0, v25
	v_rcp_f32_e32 v18, v18
	v_rcp_f32_e32 v19, v19
	v_rcp_f32_e32 v20, v20
	v_rcp_f32_e32 v21, v21
	v_rcp_f32_e32 v22, v22
	v_rcp_f32_e32 v23, v23
	v_rcp_f32_e32 v24, v24
	v_rcp_f32_e32 v25, v25
	v_mul_f32_e32 v18, v10, v18
	v_mul_f32_e32 v19, v11, v19
	v_mul_f32_e32 v20, v12, v20
	v_mul_f32_e32 v21, v13, v21
	v_mul_f32_e32 v22, v14, v22
	v_mul_f32_e32 v23, v15, v23
	v_mul_f32_e32 v24, v16, v24
	v_mul_f32_e32 v25, v17, v25
	v_mul_f32_e32 v18, v67, v18
	v_mul_f32_e32 v19, v67, v19
	v_mul_f32_e32 v20, v67, v20
	v_mul_f32_e32 v21, v67, v21
	v_mul_f32_e32 v22, v67, v22
	v_mul_f32_e32 v23, v67, v23
	v_mul_f32_e32 v24, v67, v24
	v_mul_f32_e32 v25, v67, v25
	v_cvt_pk_bf16_f32 v10, v18, v19
	v_cvt_pk_bf16_f32 v11, v20, v21
	v_cvt_pk_bf16_f32 v12, v22, v23
	v_cvt_pk_bf16_f32 v13, v24, v25
	global_store_dwordx4 v68, v[10:13], s[100:101]
	s_branch .LBB0_1611
.Lqkc_tail_zx:
	s_waitcnt vmcnt(0)
	s_bitcmp1_b32 s99, 4
	s_cbranch_scc0 .Lqkc_off0_6
	v_lshlrev_b32_e32 v59, 16, v26
	v_and_b32_e32 v60, 0xffff0000, v26
	v_lshlrev_b32_e32 v61, 16, v27
	v_and_b32_e32 v62, 0xffff0000, v27
	v_lshlrev_b32_e32 v63, 16, v28
	v_and_b32_e32 v64, 0xffff0000, v28
	v_lshlrev_b32_e32 v65, 16, v29
	v_and_b32_e32 v66, 0xffff0000, v29
	v_fma_f32 v10, v82, v59, v74
	v_fma_f32 v11, v83, v60, v75
	v_fma_f32 v12, v84, v61, v76
	v_fma_f32 v13, v85, v62, v77
	v_fma_f32 v14, v86, v63, v78
	v_fma_f32 v15, v87, v64, v79
	v_fma_f32 v16, v88, v65, v80
	v_fma_f32 v17, v89, v66, v81
	s_branch .Lqkc_j0_6

.Lqkc_off2_6:
	v_mul_f32_e32 v18, 0xbfb8aa3b, v10
	v_mul_f32_e32 v19, 0xbfb8aa3b, v11
	v_mul_f32_e32 v20, 0xbfb8aa3b, v12
	v_mul_f32_e32 v21, 0xbfb8aa3b, v13
	v_mul_f32_e32 v22, 0xbfb8aa3b, v14
	v_mul_f32_e32 v23, 0xbfb8aa3b, v15
	v_mul_f32_e32 v24, 0xbfb8aa3b, v16
	v_mul_f32_e32 v25, 0xbfb8aa3b, v17
	v_exp_f32_e32 v18, v18
	v_exp_f32_e32 v19, v19
	v_exp_f32_e32 v20, v20
	v_exp_f32_e32 v21, v21
	v_exp_f32_e32 v22, v22
	v_exp_f32_e32 v23, v23
	v_exp_f32_e32 v24, v24
	v_exp_f32_e32 v25, v25
	v_add_f32_e32 v18, 1.0, v18
	v_add_f32_e32 v19, 1.0, v19
	v_add_f32_e32 v20, 1.0, v20
	v_add_f32_e32 v21, 1.0, v21
	v_add_f32_e32 v22, 1.0, v22
	v_add_f32_e32 v23, 1.0, v23
	v_add_f32_e32 v24, 1.0, v24
	v_add_f32_e32 v25, 1.0, v25
	v_rcp_f32_e32 v18, v18
	v_rcp_f32_e32 v19, v19
	v_rcp_f32_e32 v20, v20
	v_rcp_f32_e32 v21, v21
	v_rcp_f32_e32 v22, v22
	v_rcp_f32_e32 v23, v23
	v_rcp_f32_e32 v24, v24
	v_rcp_f32_e32 v25, v25
	v_mul_f32_e32 v18, v10, v18
	v_mul_f32_e32 v19, v11, v19
	v_mul_f32_e32 v20, v12, v20
	v_mul_f32_e32 v21, v13, v21
	v_mul_f32_e32 v22, v14, v22
	v_mul_f32_e32 v23, v15, v23
	v_mul_f32_e32 v24, v16, v24
	v_mul_f32_e32 v25, v17, v25
	v_mul_f32_e32 v18, v67, v18
	v_mul_f32_e32 v19, v67, v19
	v_mul_f32_e32 v20, v67, v20
	v_mul_f32_e32 v21, v67, v21
	v_mul_f32_e32 v22, v67, v22
	v_mul_f32_e32 v23, v67, v23
	v_mul_f32_e32 v24, v67, v24
	v_mul_f32_e32 v25, v67, v25
	v_cvt_pk_bf16_f32 v10, v18, v19
	v_cvt_pk_bf16_f32 v11, v20, v21
	v_cvt_pk_bf16_f32 v12, v22, v23
	v_cvt_pk_bf16_f32 v13, v24, v25
	global_store_dwordx4 v68, v[10:13], s[100:101]

.Lqkc_off2_7:
	v_mul_f32_e32 v18, 0xbfb8aa3b, v10
	v_mul_f32_e32 v19, 0xbfb8aa3b, v11
	v_mul_f32_e32 v20, 0xbfb8aa3b, v12
	v_mul_f32_e32 v21, 0xbfb8aa3b, v13
	v_mul_f32_e32 v22, 0xbfb8aa3b, v14
	v_mul_f32_e32 v23, 0xbfb8aa3b, v15
	v_mul_f32_e32 v24, 0xbfb8aa3b, v16
	v_mul_f32_e32 v25, 0xbfb8aa3b, v17
	v_exp_f32_e32 v18, v18
	v_exp_f32_e32 v19, v19
	v_exp_f32_e32 v20, v20
	v_exp_f32_e32 v21, v21
	v_exp_f32_e32 v22, v22
	v_exp_f32_e32 v23, v23
	v_exp_f32_e32 v24, v24
	v_exp_f32_e32 v25, v25
	v_add_f32_e32 v18, 1.0, v18
	v_add_f32_e32 v19, 1.0, v19
	v_add_f32_e32 v20, 1.0, v20
	v_add_f32_e32 v21, 1.0, v21
	v_add_f32_e32 v22, 1.0, v22
	v_add_f32_e32 v23, 1.0, v23
	v_add_f32_e32 v24, 1.0, v24
	v_add_f32_e32 v25, 1.0, v25
	v_rcp_f32_e32 v18, v18
	v_rcp_f32_e32 v19, v19
	v_rcp_f32_e32 v20, v20
	v_rcp_f32_e32 v21, v21
	v_rcp_f32_e32 v22, v22
	v_rcp_f32_e32 v23, v23
	v_rcp_f32_e32 v24, v24
	v_rcp_f32_e32 v25, v25
	v_mul_f32_e32 v18, v10, v18
	v_mul_f32_e32 v19, v11, v19
	v_mul_f32_e32 v20, v12, v20
	v_mul_f32_e32 v21, v13, v21
	v_mul_f32_e32 v22, v14, v22
	v_mul_f32_e32 v23, v15, v23
	v_mul_f32_e32 v24, v16, v24
	v_mul_f32_e32 v25, v17, v25
	v_mul_f32_e32 v18, v67, v18
	v_mul_f32_e32 v19, v67, v19
	v_mul_f32_e32 v20, v67, v20
	v_mul_f32_e32 v21, v67, v21
	v_mul_f32_e32 v22, v67, v22
	v_mul_f32_e32 v23, v67, v23
	v_mul_f32_e32 v24, v67, v24
	v_mul_f32_e32 v25, v67, v25
	v_cvt_pk_bf16_f32 v10, v18, v19
	v_cvt_pk_bf16_f32 v11, v20, v21
	v_cvt_pk_bf16_f32 v12, v22, v23
	v_cvt_pk_bf16_f32 v13, v24, v25
	global_store_dwordx4 v68, v[10:13], s[10:11]
	s_branch .LBB0_1611
.Lqkc_tail_xy:
	s_waitcnt vmcnt(0)
	s_bitcmp1_b32 s99, 0
	s_cbranch_scc0 .Lqkc_off0_8
	v_lshlrev_b32_e32 v59, 16, v46
	v_and_b32_e32 v60, 0xffff0000, v46
	v_lshlrev_b32_e32 v61, 16, v47
	v_and_b32_e32 v62, 0xffff0000, v47
	v_lshlrev_b32_e32 v63, 16, v48
	v_and_b32_e32 v64, 0xffff0000, v48
	v_lshlrev_b32_e32 v65, 16, v49
	v_and_b32_e32 v66, 0xffff0000, v49
	v_fma_f32 v10, v82, v59, v74
	v_fma_f32 v11, v83, v60, v75
	v_fma_f32 v12, v84, v61, v76
	v_fma_f32 v13, v85, v62, v77
	v_fma_f32 v14, v86, v63, v78
	v_fma_f32 v15, v87, v64, v79
	v_fma_f32 v16, v88, v65, v80
	v_fma_f32 v17, v89, v66, v81
	s_branch .Lqkc_j0_8

.Lqkc_off2_8:
	v_mul_f32_e32 v18, 0xbfb8aa3b, v10
	v_mul_f32_e32 v19, 0xbfb8aa3b, v11
	v_mul_f32_e32 v20, 0xbfb8aa3b, v12
	v_mul_f32_e32 v21, 0xbfb8aa3b, v13
	v_mul_f32_e32 v22, 0xbfb8aa3b, v14
	v_mul_f32_e32 v23, 0xbfb8aa3b, v15
	v_mul_f32_e32 v24, 0xbfb8aa3b, v16
	v_mul_f32_e32 v25, 0xbfb8aa3b, v17
	v_exp_f32_e32 v18, v18
	v_exp_f32_e32 v19, v19
	v_exp_f32_e32 v20, v20
	v_exp_f32_e32 v21, v21
	v_exp_f32_e32 v22, v22
	v_exp_f32_e32 v23, v23
	v_exp_f32_e32 v24, v24
	v_exp_f32_e32 v25, v25
	v_add_f32_e32 v18, 1.0, v18
	v_add_f32_e32 v19, 1.0, v19
	v_add_f32_e32 v20, 1.0, v20
	v_add_f32_e32 v21, 1.0, v21
	v_add_f32_e32 v22, 1.0, v22
	v_add_f32_e32 v23, 1.0, v23
	v_add_f32_e32 v24, 1.0, v24
	v_add_f32_e32 v25, 1.0, v25
	v_rcp_f32_e32 v18, v18
	v_rcp_f32_e32 v19, v19
	v_rcp_f32_e32 v20, v20
	v_rcp_f32_e32 v21, v21
	v_rcp_f32_e32 v22, v22
	v_rcp_f32_e32 v23, v23
	v_rcp_f32_e32 v24, v24
	v_rcp_f32_e32 v25, v25
	v_mul_f32_e32 v18, v10, v18
	v_mul_f32_e32 v19, v11, v19
	v_mul_f32_e32 v20, v12, v20
	v_mul_f32_e32 v21, v13, v21
	v_mul_f32_e32 v22, v14, v22
	v_mul_f32_e32 v23, v15, v23
	v_mul_f32_e32 v24, v16, v24
	v_mul_f32_e32 v25, v17, v25
	v_mul_f32_e32 v18, v67, v18
	v_mul_f32_e32 v19, v67, v19
	v_mul_f32_e32 v20, v67, v20
	v_mul_f32_e32 v21, v67, v21
	v_mul_f32_e32 v22, v67, v22
	v_mul_f32_e32 v23, v67, v23
	v_mul_f32_e32 v24, v67, v24
	v_mul_f32_e32 v25, v67, v25
	v_cvt_pk_bf16_f32 v10, v18, v19
	v_cvt_pk_bf16_f32 v11, v20, v21
	v_cvt_pk_bf16_f32 v12, v22, v23
	v_cvt_pk_bf16_f32 v13, v24, v25
	global_store_dwordx4 v68, v[10:13], s[10:11]
	s_waitcnt vmcnt(0)
	s_bitcmp1_b32 s99, 2
	s_cbranch_scc0 .Lqkc_off0_9
	v_lshlrev_b32_e32 v59, 16, v114
	v_and_b32_e32 v60, 0xffff0000, v114
	v_lshlrev_b32_e32 v61, 16, v115
	v_and_b32_e32 v62, 0xffff0000, v115
	v_lshlrev_b32_e32 v63, 16, v116
	v_and_b32_e32 v64, 0xffff0000, v116
	v_lshlrev_b32_e32 v65, 16, v117
	v_and_b32_e32 v66, 0xffff0000, v117
	v_fma_f32 v10, v82, v59, v74
	v_fma_f32 v11, v83, v60, v75
	v_fma_f32 v12, v84, v61, v76
	v_fma_f32 v13, v85, v62, v77
	v_fma_f32 v14, v86, v63, v78
	v_fma_f32 v15, v87, v64, v79
	v_fma_f32 v16, v88, v65, v80
	v_fma_f32 v17, v89, v66, v81
	s_branch .Lqkc_j0_9
